# combined LRU reductions + the 16 now-unused forward LDS reads removed (waits recomputed)
# speedup vs baseline: 1.0102x; 1.0102x over previous
; #define LAS __attribute__((address_space(3)))
; template <int dir>
; __device__ __forceinline__ void lru_pass(LAS unsigned char* lds, const Params& P, int b, int h, int q, bool dry) {
;     ...
;             const int sbase = 32 * wid + 16 * g;
;             { const int sl = 32 * wid + s_i; const int tlA = dir == 0 ? sl : 255 - sl;
;               const LAS unsigned char* ap = XC + tlA * XC_PITCH + 16 * g;
;               const LAS unsigned char* wrp = WB + nl * XC_PITCH + 16 * g; const LAS unsigned char* wip = wrp + 32 * XC_PITCH;
; #pragma unroll
;               for (int ks = 0; ks < 8; ++ks) { const bf16x8 A = *(const LAS bf16x8*)(ap + 32 * ks);
;                   const bf16x8 Br = *(const LAS bf16x8*)(wrp + 32 * ks), Bi = *(const LAS bf16x8*)(wip + 32 * ks);
;                   zr = __builtin_amdgcn_mfma_f32_32x32x16_bf16(A, Br, zr, 0, 0, 0); zi = __builtin_amdgcn_mfma_f32_32x32x16_bf16(A, Bi, zi, 0, 0, 0); } }
;             unsigned xcb[16], pk[16];
; #pragma unroll
;             for (int v = 0; v < 16; ++v) { const int s = sbase + v; const int tl = dir == 0 ? s : 255 - s; xcb[v] = *(const LAS bf16_t*)(XC + tl * XC_PITCH + chl * 2);
;                 if (dir == 0) pk[v] = *(const LAS bf16_t*)(TIN + tl * IO_NP + nl * 2); else pk[v] = *(const LAS unsigned*)(TIN + tl * IO_WP + nl * 4); }
;             float Pp = 1.f, E = 0.f;
; #pragma unroll
;             for (int v = 0; v < 16; ++v) {
;                 const float xcv = __uint_as_float(xcb[v] << 16);
;                 const float r = __builtin_amdgcn_rcpf(1.0f + __builtin_amdgcn_exp2f(zr[v]));
;                 const float ig = __builtin_amdgcn_rcpf(1.0f + __builtin_amdgcn_exp2f(zi[v]));
;                 const float a = __builtin_amdgcn_exp2f(cl * r);
;                 const float sq = __builtin_amdgcn_sqrtf(fmaf(-a, a, 1.0f));
;                 const float u = sq * ig * xcv;
;                 E = fmaf(a, E, u); Pp *= a; zr[v] = E; zi[v] = Pp; }
.Llruf_wres:
	ds_read_b128 v[120:123], v160
	ds_read_b128 v[124:127], v160 offset:32
	ds_read_b128 v[168:171], v160 offset:64
	ds_read_b128 v[172:175], v160 offset:96
	ds_read_b128 v[176:179], v160 offset:128
	ds_read_b128 v[180:183], v160 offset:160
	ds_read_b128 v[184:187], v160 offset:192
	ds_read_b128 v[188:191], v160 offset:224
	ds_read_b128 v[236:239], v161 offset:8704
	ds_read_b128 v[240:243], v161 offset:8736
	ds_read_b128 v[244:247], v161 offset:8768
	ds_read_b128 v[248:251], v161 offset:8800
	s_waitcnt lgkmcnt(11)
	v_mfma_f32_32x32x16_bf16 v[32:47], v[120:123], v[204:207], v[0:15]
	s_waitcnt lgkmcnt(10)
	v_mfma_f32_32x32x16_bf16 v[32:47], v[124:127], v[208:211], v[32:47]
	s_waitcnt lgkmcnt(9)
	v_mfma_f32_32x32x16_bf16 v[32:47], v[168:171], v[212:215], v[32:47]
	s_waitcnt lgkmcnt(8)
	v_mfma_f32_32x32x16_bf16 v[32:47], v[172:175], v[216:219], v[32:47]
	s_waitcnt lgkmcnt(7)
	v_mfma_f32_32x32x16_bf16 v[32:47], v[176:179], v[220:223], v[32:47]
	s_waitcnt lgkmcnt(6)
	v_mfma_f32_32x32x16_bf16 v[32:47], v[180:183], v[224:227], v[32:47]
	s_waitcnt lgkmcnt(5)
	v_mfma_f32_32x32x16_bf16 v[32:47], v[184:187], v[228:231], v[32:47]
	s_waitcnt lgkmcnt(4)
	v_mfma_f32_32x32x16_bf16 v[32:47], v[188:191], v[232:235], v[32:47]
	s_waitcnt lgkmcnt(3)
	v_mfma_f32_32x32x16_bf16 v[48:63], v[120:123], v[236:239], v[16:31]
	ds_read_b128 v[236:239], v161 offset:8832
	s_nop 8
	v_exp_f32_e32 v32, v32
	v_exp_f32_e32 v33, v33
	v_exp_f32_e32 v34, v34
	v_fma_f32 v32, v32, v138, v138
	v_rcp_f32_e32 v32, v32
	s_waitcnt lgkmcnt(3)
	v_mfma_f32_32x32x16_bf16 v[48:63], v[124:127], v[240:243], v[48:63]
	ds_read_b128 v[240:243], v161 offset:8864
	v_fma_f32 v33, v33, v138, v138
	v_rcp_f32_e32 v33, v33
	s_nop 0
	s_waitcnt lgkmcnt(3)
	v_mfma_f32_32x32x16_bf16 v[48:63], v[168:171], v[244:247], v[48:63]
	ds_read_b128 v[244:247], v161 offset:8896
	v_exp_f32_e32 v33, v33
	s_waitcnt lgkmcnt(3)
	v_mfma_f32_32x32x16_bf16 v[48:63], v[172:175], v[248:251], v[48:63]
	ds_read_b128 v[248:251], v161 offset:8928
	ds_read_u16 v152, v162
	ds_read_u16 v154, v162 offset:272
	ds_read_u16 v155, v162 offset:544
	ds_read_u16 v157, v162 offset:816
	ds_read_u16 v196, v162 offset:1088
	ds_read_u16 v197, v162 offset:1360
	s_waitcnt lgkmcnt(5)
	v_lshlrev_b32_e32 v152, 16, v152
	s_waitcnt lgkmcnt(4)
	v_lshlrev_b32_e32 v154, 16, v154
	v_mfma_f32_32x32x16_bf16 v[48:63], v[176:179], v[236:239], v[48:63]
	ds_read_u16 v177, v162 offset:1632
	ds_read_u16 v178, v162 offset:1904
	s_nop 0
	v_mfma_f32_32x32x16_bf16 v[48:63], v[180:183], v[240:243], v[48:63]
	v_exp_f32_e32 v171, v32
	ds_read_u16 v179, v162 offset:2176
	ds_read_u16 v180, v162 offset:2448
	ds_read_u16 v181, v162 offset:2720
	v_mfma_f32_32x32x16_bf16 v[48:63], v[184:187], v[244:247], v[48:63]
	ds_read_u16 v182, v162 offset:2992
	ds_read_u16 v183, v162 offset:3264
	ds_read_u16 v184, v162 offset:3536
	ds_read_u16 v185, v162 offset:3808
	ds_read_u16 v187, v162 offset:4080
	v_mfma_f32_32x32x16_bf16 v[48:63], v[188:191], v[248:251], v[48:63]
	s_nop 11
	v_exp_f32_e32 v172, v48
	s_nop 0
	v_add_f32_e32 v32, 1.0, v172
	v_fma_f32 v172, -v171, v171, 1.0
	v_rcp_f32_e32 v32, v32
	v_sqrt_f32_e32 v172, v172
	s_nop 0
	v_mul_f32_e32 v32, v172, v32
	v_exp_f32_e32 v172, v49
	v_mul_f32_e32 v49, v32, v152
	v_fma_f32 v152, -v33, v33, 1.0
	v_sqrt_f32_e32 v152, v152
	v_add_f32_e32 v32, 1.0, v172
	v_rcp_f32_e32 v32, v32
	v_fmac_f32_e32 v49, 0, v171
	v_mul_f32_e32 v32, v152, v32
	v_mul_f32_e32 v172, v32, v154
	v_fma_f32 v32, v34, v138, v138
	v_rcp_f32_e32 v32, v32
	v_exp_f32_e32 v34, v50
	v_fmac_f32_e32 v172, v33, v49
	v_mul_f32_e32 v50, v171, v33
	v_exp_f32_e32 v32, v32
	v_add_f32_e32 v33, 1.0, v34
	v_exp_f32_e32 v34, v35
	v_rcp_f32_e32 v33, v33
	v_fma_f32 v35, -v32, v32, 1.0
	v_sqrt_f32_e32 v35, v35
	v_fma_f32 v34, v34, v138, v138
	v_rcp_f32_e32 v34, v34
	s_waitcnt lgkmcnt(6)
; template <int dir>
; __device__ __forceinline__ void lru_pass(LAS unsigned char* lds, const Params& P, int b, int h, int q, bool dry) {
;     ...
;             float Pp = 1.f, E = 0.f;
; #pragma unroll
;             for (int v = 0; v < 16; ++v) {
;                 const float xcv = __uint_as_float(xcb[v] << 16);
;                 const float r = __builtin_amdgcn_rcpf(1.0f + __builtin_amdgcn_exp2f(zr[v]));
;                 const float ig = __builtin_amdgcn_rcpf(1.0f + __builtin_amdgcn_exp2f(zi[v]));
;                 const float a = __builtin_amdgcn_exp2f(cl * r);
;                 const float sq = __builtin_amdgcn_sqrtf(fmaf(-a, a, 1.0f));
;                 const float u = sq * ig * xcv;
;                 E = fmaf(a, E, u); Pp *= a; zr[v] = E; zi[v] = Pp; }
;             const float Po = __shfl_xor(Pp, 32), Eo = __shfl_xor(E, 32);
;             const float P0 = g ? Po : Pp, E0 = g ? Eo : E, P1 = g ? Pp : Po, E1 = g ? E : Eo;
;             if (g == 0) { AGG[(wid * 2 + 0) * 32 + nl] = P0 * P1; AGG[(wid * 2 + 1) * 32 + nl] = fmaf(P1, E0, E1); }
	v_lshlrev_b32_e32 v152, 16, v155
	v_mul_f32_e32 v33, v35, v33
	v_mul_f32_e32 v173, v33, v152
	v_exp_f32_e32 v33, v51
	v_exp_f32_e32 v34, v34
	v_fmac_f32_e32 v173, v32, v172
	v_mul_f32_e32 v51, v32, v50
	v_exp_f32_e32 v32, v36
	v_add_f32_e32 v33, 1.0, v33
	v_fma_f32 v35, -v34, v34, 1.0
	v_rcp_f32_e32 v33, v33
	v_sqrt_f32_e32 v35, v35
	v_fma_f32 v32, v32, v138, v138
	v_rcp_f32_e32 v32, v32
	v_lshlrev_b32_e32 v36, 16, v157
	v_mul_f32_e32 v33, v35, v33
	v_mul_f32_e32 v174, v33, v36
	v_fmac_f32_e32 v174, v34, v173
	v_exp_f32_e32 v33, v52
	v_mul_f32_e32 v52, v34, v51
	v_exp_f32_e32 v32, v32
	v_exp_f32_e32 v34, v37
	v_add_f32_e32 v33, 1.0, v33
	v_rcp_f32_e32 v33, v33
	v_fma_f32 v35, -v32, v32, 1.0
	v_fma_f32 v34, v34, v138, v138
	v_sqrt_f32_e32 v35, v35
	v_rcp_f32_e32 v34, v34
	v_lshlrev_b32_e32 v36, 16, v196
	v_mul_f32_e32 v33, v35, v33
	v_mul_f32_e32 v175, v33, v36
	v_exp_f32_e32 v33, v53
	v_exp_f32_e32 v34, v34
	v_fmac_f32_e32 v175, v32, v174
	v_mul_f32_e32 v53, v32, v52
	v_exp_f32_e32 v32, v38
	v_add_f32_e32 v33, 1.0, v33
	v_fma_f32 v35, -v34, v34, 1.0
	v_rcp_f32_e32 v33, v33
	v_sqrt_f32_e32 v35, v35
	v_fma_f32 v32, v32, v138, v138
	v_rcp_f32_e32 v32, v32
	v_lshlrev_b32_e32 v36, 16, v197
	v_mul_f32_e32 v33, v35, v33
	v_mul_f32_e32 v176, v33, v36
	v_fmac_f32_e32 v176, v34, v175
	v_exp_f32_e32 v33, v54
	v_mul_f32_e32 v54, v34, v53
	v_exp_f32_e32 v32, v32
	v_exp_f32_e32 v34, v39
	v_add_f32_e32 v33, 1.0, v33
	v_rcp_f32_e32 v33, v33
	v_fma_f32 v35, -v32, v32, 1.0
	v_fma_f32 v34, v34, v138, v138
	v_sqrt_f32_e32 v35, v35
	v_rcp_f32_e32 v34, v34
	v_lshlrev_b32_e32 v36, 16, v177
	v_mul_f32_e32 v33, v35, v33
	v_mul_f32_e32 v177, v33, v36
	v_exp_f32_e32 v33, v55
	v_exp_f32_e32 v34, v34
	v_fmac_f32_e32 v177, v32, v176
	v_mul_f32_e32 v55, v32, v54
	v_exp_f32_e32 v32, v40
	v_add_f32_e32 v33, 1.0, v33
	v_fma_f32 v35, -v34, v34, 1.0
	v_rcp_f32_e32 v33, v33
	v_sqrt_f32_e32 v35, v35
	v_fma_f32 v32, v32, v138, v138
	v_rcp_f32_e32 v32, v32
	v_lshlrev_b32_e32 v36, 16, v178
	v_mul_f32_e32 v33, v35, v33
	v_mul_f32_e32 v178, v33, v36
	v_fmac_f32_e32 v178, v34, v177
	v_exp_f32_e32 v33, v56
	v_mul_f32_e32 v56, v34, v55
	v_exp_f32_e32 v32, v32
	v_exp_f32_e32 v34, v41
	v_add_f32_e32 v33, 1.0, v33
	v_rcp_f32_e32 v33, v33
	v_fma_f32 v35, -v32, v32, 1.0
	v_fma_f32 v34, v34, v138, v138
	v_sqrt_f32_e32 v35, v35
	v_rcp_f32_e32 v34, v34
	v_lshlrev_b32_e32 v36, 16, v179
	v_mul_f32_e32 v33, v35, v33
	v_mul_f32_e32 v179, v33, v36
	v_exp_f32_e32 v33, v57
	v_exp_f32_e32 v34, v34
	v_fmac_f32_e32 v179, v32, v178
	v_mul_f32_e32 v57, v32, v56
	v_exp_f32_e32 v32, v42
	v_add_f32_e32 v33, 1.0, v33
	v_fma_f32 v35, -v34, v34, 1.0
	v_rcp_f32_e32 v33, v33
	v_sqrt_f32_e32 v35, v35
	v_fma_f32 v32, v32, v138, v138
	v_rcp_f32_e32 v32, v32
	v_lshlrev_b32_e32 v36, 16, v180
	v_mul_f32_e32 v33, v35, v33
	v_mul_f32_e32 v180, v33, v36
	v_fmac_f32_e32 v180, v34, v179
	v_exp_f32_e32 v33, v58
	v_mul_f32_e32 v58, v34, v57
	v_exp_f32_e32 v32, v32
	v_exp_f32_e32 v34, v43
	v_add_f32_e32 v33, 1.0, v33
	v_rcp_f32_e32 v33, v33
	v_fma_f32 v35, -v32, v32, 1.0
	v_fma_f32 v34, v34, v138, v138
	v_sqrt_f32_e32 v35, v35
	v_rcp_f32_e32 v34, v34
	s_waitcnt lgkmcnt(5)
	v_lshlrev_b32_e32 v36, 16, v181
	v_mul_f32_e32 v33, v35, v33
	v_mul_f32_e32 v181, v33, v36
	v_exp_f32_e32 v33, v59
	v_exp_f32_e32 v34, v34
	v_fmac_f32_e32 v181, v32, v180
	v_mul_f32_e32 v59, v32, v58
	v_exp_f32_e32 v32, v44
	v_add_f32_e32 v33, 1.0, v33
	v_fma_f32 v35, -v34, v34, 1.0
	v_rcp_f32_e32 v33, v33
	v_sqrt_f32_e32 v35, v35
	v_fma_f32 v32, v32, v138, v138
	v_rcp_f32_e32 v32, v32
	s_waitcnt lgkmcnt(4)
	v_lshlrev_b32_e32 v36, 16, v182
	v_mul_f32_e32 v33, v35, v33
	v_mul_f32_e32 v182, v33, v36
	v_fmac_f32_e32 v182, v34, v181
	v_exp_f32_e32 v33, v60
	v_mul_f32_e32 v60, v34, v59
	v_exp_f32_e32 v32, v32
	v_exp_f32_e32 v34, v45
	v_add_f32_e32 v33, 1.0, v33
	v_rcp_f32_e32 v33, v33
	v_fma_f32 v35, -v32, v32, 1.0
	v_fma_f32 v34, v34, v138, v138
	v_sqrt_f32_e32 v35, v35
	v_rcp_f32_e32 v34, v34
	s_waitcnt lgkmcnt(3)
	v_lshlrev_b32_e32 v36, 16, v183
	v_mul_f32_e32 v33, v35, v33
	v_mul_f32_e32 v183, v33, v36
	v_exp_f32_e32 v33, v61
	v_exp_f32_e32 v34, v34
	v_fmac_f32_e32 v183, v32, v182
	v_mul_f32_e32 v61, v32, v60
	v_exp_f32_e32 v32, v46
	v_add_f32_e32 v33, 1.0, v33
	v_fma_f32 v35, -v34, v34, 1.0
	v_rcp_f32_e32 v33, v33
	v_sqrt_f32_e32 v35, v35
	v_fma_f32 v32, v32, v138, v138
	v_rcp_f32_e32 v32, v32
	s_waitcnt lgkmcnt(2)
	v_lshlrev_b32_e32 v36, 16, v184
	v_mul_f32_e32 v33, v35, v33
	v_mul_f32_e32 v184, v33, v36
	v_fmac_f32_e32 v184, v34, v183
	v_exp_f32_e32 v33, v62
	v_mul_f32_e32 v62, v34, v61
	v_exp_f32_e32 v34, v47
	v_exp_f32_e32 v32, v32
	v_add_f32_e32 v33, 1.0, v33
	v_rcp_f32_e32 v33, v33
	v_fma_f32 v34, v34, v138, v138
	v_fma_f32 v35, -v32, v32, 1.0
	v_rcp_f32_e32 v34, v34
	v_sqrt_f32_e32 v35, v35
	s_waitcnt lgkmcnt(1)
	v_lshlrev_b32_e32 v36, 16, v185
	v_mul_f32_e32 v186, v32, v62
	v_mul_f32_e32 v33, v35, v33
	v_exp_f32_e32 v35, v63
	v_exp_f32_e32 v34, v34
	v_mul_f32_e32 v63, v33, v36
	v_fmac_f32_e32 v63, v32, v184
	v_add_f32_e32 v33, 1.0, v35
	v_fma_f32 v35, -v34, v34, 1.0
	v_rcp_f32_e32 v33, v33
	v_sqrt_f32_e32 v35, v35
	s_waitcnt lgkmcnt(0)
	v_lshlrev_b32_e32 v32, 16, v187
	v_mul_f32_e32 v187, v34, v186
	v_mul_f32_e32 v33, v35, v33
	v_mul_f32_e32 v185, v33, v32
	v_fmac_f32_e32 v185, v34, v63
	v_mov_b32_e32 v188, v187
	v_mov_b32_e32 v252, v187
	v_mov_b32_e32 v189, v185
	v_mov_b32_e32 v253, v185
	s_nop 1
	v_permlane32_swap_b32 v188, v252
	v_permlane32_swap_b32 v189, v253
	s_and_saveexec_b64 s[18:19], vcc
	s_cbranch_execz .LBB0_299
	v_fma_f32 v32, v252, v189, v253
	v_mul_f32_e32 v33, v188, v252
	v_add_u32_e32 v35, s98, v147
	ds_write2_b32 v35, v33, v32 offset1:32
